# MLA k / v GEMM epilogues: per-row rstd scale loaded once per row instead of once per fragment
# baseline (speedup 1.0000x reference)
.LBB0_2610:
	s_ashr_i32 s8, s7, 31
	s_lshr_b32 s8, s8, 29
	s_add_i32 s8, s7, s8
	s_ashr_i32 s8, s8, 3
	s_lshl_b32 s12, s8, 8
	s_lshl_b32 s8, s8, 10
	s_sub_i32 s10, s2, s8
	s_ashr_i32 s13, s12, 31
	s_ashr_i32 s11, s10, 31
	s_lshl_b64 s[8:9], s[12:13], 9
	s_lshl_b64 s[14:15], s[10:11], 9
	v_lshl_add_u64 v[6:7], v[10:11], 0, s[8:9]
	v_lshl_add_u64 v[24:25], v[12:13], 0, s[14:15]
	v_lshl_add_u64 v[0:1], v[6:7], 0, v[14:15]
	v_lshl_add_u64 v[22:23], v[24:25], 0, v[14:15]
	v_lshl_add_u64 v[4:5], v[6:7], 0, v[16:17]
	v_lshl_add_u64 v[2:3], v[6:7], 0, v[18:19]
	v_lshl_add_u64 v[6:7], v[6:7], 0, v[20:21]
	global_load_dwordx4 v[34:37], v[0:1], off
	global_load_dwordx4 v[38:41], v[4:5], off
	global_load_dwordx4 v[42:45], v[2:3], off
	global_load_dwordx4 v[46:49], v[6:7], off
	v_lshl_add_u64 v[24:25], v[24:25], 0, v[16:17]
	global_load_dwordx4 v[50:53], v[22:23], off
	global_load_dwordx4 v[54:57], v[24:25], off
	s_barrier
	v_or_b32_e32 v33, s12, v26
	s_add_i32 s7, s7, s82
	s_add_i32 s2, s2, s4
	s_cmpk_lt_i32 s7, 0x420
	s_waitcnt vmcnt(5)
	ds_write_b128 v28, v[34:37]
	s_waitcnt vmcnt(4)
	ds_write_b128 v29, v[38:41]
	s_waitcnt vmcnt(3)
	ds_write_b128 v28, v[42:45] offset:18432
	s_waitcnt vmcnt(2)
	ds_write_b128 v30, v[46:49]
	s_waitcnt vmcnt(1)
	ds_write_b128 v28, v[50:53] offset:36864
	s_waitcnt vmcnt(0)
	ds_write_b128 v29, v[54:57] offset:36864
	s_waitcnt lgkmcnt(0)
	s_barrier
	ds_read_b128 v[34:37], v32 offset:36864
	ds_read_b128 v[38:41], v31
	ds_read_b128 v[42:45], v31 offset:64
	ds_read_b128 v[46:49], v32 offset:36928
	ds_read_b128 v[54:57], v32 offset:39168
	ds_read_b128 v[58:61], v32 offset:39232
	ds_read_b128 v[66:69], v32 offset:41472
	ds_read_b128 v[70:73], v32 offset:41536
	ds_read_b128 v[78:81], v32 offset:43776
	ds_read_b128 v[82:85], v32 offset:43840
	ds_read_b128 v[86:89], v31 offset:2304
	ds_read_b128 v[90:93], v31 offset:2368
	ds_read_b128 v[106:109], v31 offset:4608
	ds_read_b128 v[110:113], v31 offset:4672
	ds_read_b128 v[126:129], v31 offset:6912
	ds_read_b128 v[130:133], v31 offset:6976
	s_waitcnt lgkmcnt(14)
	v_mfma_f32_16x16x32_bf16 v[50:53], v[34:37], v[38:41], 0
	s_waitcnt lgkmcnt(11)
	v_mfma_f32_16x16x32_bf16 v[62:65], v[54:57], v[38:41], 0
	s_waitcnt lgkmcnt(9)
	v_mfma_f32_16x16x32_bf16 v[74:77], v[66:69], v[38:41], 0
	s_waitcnt lgkmcnt(7)
	v_mfma_f32_16x16x32_bf16 v[38:41], v[78:81], v[38:41], 0
	s_waitcnt lgkmcnt(5)
	v_mfma_f32_16x16x32_bf16 v[94:97], v[34:37], v[86:89], 0
	v_mfma_f32_16x16x32_bf16 v[98:101], v[54:57], v[86:89], 0
	v_mfma_f32_16x16x32_bf16 v[102:105], v[66:69], v[86:89], 0
	v_mfma_f32_16x16x32_bf16 v[86:89], v[78:81], v[86:89], 0
	s_waitcnt lgkmcnt(3)
	v_mfma_f32_16x16x32_bf16 v[114:117], v[34:37], v[106:109], 0
	v_mfma_f32_16x16x32_bf16 v[118:121], v[54:57], v[106:109], 0
	v_mfma_f32_16x16x32_bf16 v[122:125], v[66:69], v[106:109], 0
	v_mfma_f32_16x16x32_bf16 v[106:109], v[78:81], v[106:109], 0
	s_waitcnt lgkmcnt(1)
	v_mfma_f32_16x16x32_bf16 v[34:37], v[34:37], v[126:129], 0
	v_mfma_f32_16x16x32_bf16 v[54:57], v[54:57], v[126:129], 0
	v_mfma_f32_16x16x32_bf16 v[66:69], v[66:69], v[126:129], 0
	v_mfma_f32_16x16x32_bf16 v[78:81], v[78:81], v[126:129], 0
	v_mfma_f32_16x16x32_bf16 v[50:53], v[46:49], v[42:45], v[50:53]
	v_mfma_f32_16x16x32_bf16 v[62:65], v[58:61], v[42:45], v[62:65]
	v_mfma_f32_16x16x32_bf16 v[74:77], v[70:73], v[42:45], v[74:77]
	v_mfma_f32_16x16x32_bf16 v[38:41], v[82:85], v[42:45], v[38:41]
	v_mfma_f32_16x16x32_bf16 v[42:45], v[46:49], v[90:93], v[94:97]
	v_mfma_f32_16x16x32_bf16 v[94:97], v[58:61], v[90:93], v[98:101]
	v_mfma_f32_16x16x32_bf16 v[98:101], v[70:73], v[90:93], v[102:105]
	v_mfma_f32_16x16x32_bf16 v[86:89], v[82:85], v[90:93], v[86:89]
	v_mfma_f32_16x16x32_bf16 v[90:93], v[46:49], v[110:113], v[114:117]
	v_mfma_f32_16x16x32_bf16 v[102:105], v[58:61], v[110:113], v[118:121]
	v_mfma_f32_16x16x32_bf16 v[114:117], v[70:73], v[110:113], v[122:125]
	v_mfma_f32_16x16x32_bf16 v[106:109], v[82:85], v[110:113], v[106:109]
	global_load_dwordx4 v[110:113], v[4:5], off offset:128
	global_load_dwordx4 v[118:121], v[0:1], off offset:128
	s_waitcnt lgkmcnt(0)
	v_mfma_f32_16x16x32_bf16 v[34:37], v[46:49], v[130:133], v[34:37]
	global_load_dwordx4 v[46:49], v[6:7], off offset:128
	global_load_dwordx4 v[122:125], v[2:3], off offset:128
	global_load_dwordx4 v[126:129], v[22:23], off offset:128
	v_mfma_f32_16x16x32_bf16 v[54:57], v[58:61], v[130:133], v[54:57]
	global_load_dwordx4 v[58:61], v[24:25], off offset:128
	s_barrier
	v_mfma_f32_16x16x32_bf16 v[66:69], v[70:73], v[130:133], v[66:69]
	s_waitcnt vmcnt(4)
	ds_write_b128 v28, v[118:121]
	ds_write_b128 v29, v[110:113]
	s_waitcnt vmcnt(2)
	ds_write_b128 v28, v[122:125] offset:18432
	ds_write_b128 v30, v[46:49]
	s_waitcnt vmcnt(1)
	ds_write_b128 v28, v[126:129] offset:36864
	s_waitcnt vmcnt(0)
	ds_write_b128 v29, v[58:61] offset:36864
	v_mfma_f32_16x16x32_bf16 v[70:73], v[82:85], v[130:133], v[78:81]
	s_waitcnt lgkmcnt(0)
	s_barrier
	ds_read_b128 v[46:49], v32 offset:36864
	ds_read_b128 v[58:61], v31
	ds_read_b128 v[78:81], v31 offset:64
	ds_read_b128 v[82:85], v32 offset:36928
	ds_read_b128 v[110:113], v32 offset:39168
	ds_read_b128 v[118:121], v32 offset:39232
	ds_read_b128 v[122:125], v32 offset:41472
	ds_read_b128 v[126:129], v32 offset:41536
	ds_read_b128 v[130:133], v32 offset:43776
	ds_read_b128 v[134:137], v32 offset:43840
	s_waitcnt lgkmcnt(8)
	v_mfma_f32_16x16x32_bf16 v[50:53], v[46:49], v[58:61], v[50:53]
	s_waitcnt lgkmcnt(5)
	v_mfma_f32_16x16x32_bf16 v[62:65], v[110:113], v[58:61], v[62:65]
	s_waitcnt lgkmcnt(3)
	v_mfma_f32_16x16x32_bf16 v[74:77], v[122:125], v[58:61], v[74:77]
	s_waitcnt lgkmcnt(1)
	v_mfma_f32_16x16x32_bf16 v[38:41], v[130:133], v[58:61], v[38:41]
	ds_read_b128 v[58:61], v31 offset:2304
	ds_read_b128 v[138:141], v31 offset:2368
	s_waitcnt lgkmcnt(1)
	v_mfma_f32_16x16x32_bf16 v[42:45], v[46:49], v[58:61], v[42:45]
	v_mfma_f32_16x16x32_bf16 v[94:97], v[110:113], v[58:61], v[94:97]
	v_mfma_f32_16x16x32_bf16 v[98:101], v[122:125], v[58:61], v[98:101]
	v_mfma_f32_16x16x32_bf16 v[58:61], v[130:133], v[58:61], v[86:89]
	s_nop 2
	ds_read_b128 v[86:89], v31 offset:4608
	ds_read_b128 v[158:161], v31 offset:4672
	s_waitcnt lgkmcnt(1)
	v_mfma_f32_16x16x32_bf16 v[90:93], v[46:49], v[86:89], v[90:93]
	v_mfma_f32_16x16x32_bf16 v[102:105], v[110:113], v[86:89], v[102:105]
	v_mfma_f32_16x16x32_bf16 v[114:117], v[122:125], v[86:89], v[114:117]
	v_mfma_f32_16x16x32_bf16 v[86:89], v[130:133], v[86:89], v[106:109]
	s_nop 2
	ds_read_b128 v[106:109], v31 offset:6912
	ds_read_b128 v[162:165], v31 offset:6976
	s_waitcnt lgkmcnt(1)
	v_mfma_f32_16x16x32_bf16 v[34:37], v[46:49], v[106:109], v[34:37]
	v_mfma_f32_16x16x32_bf16 v[46:49], v[110:113], v[106:109], v[54:57]
	v_mfma_f32_16x16x32_bf16 v[54:57], v[122:125], v[106:109], v[66:69]
	v_mfma_f32_16x16x32_bf16 v[66:69], v[130:133], v[106:109], v[70:73]
	v_mfma_f32_16x16x32_bf16 v[50:53], v[82:85], v[78:81], v[50:53]
	v_mfma_f32_16x16x32_bf16 v[62:65], v[118:121], v[78:81], v[62:65]
	v_mfma_f32_16x16x32_bf16 v[70:73], v[126:129], v[78:81], v[74:77]
	v_mfma_f32_16x16x32_bf16 v[38:41], v[134:137], v[78:81], v[38:41]
	v_mfma_f32_16x16x32_bf16 v[42:45], v[82:85], v[138:141], v[42:45]
	v_mfma_f32_16x16x32_bf16 v[74:77], v[118:121], v[138:141], v[94:97]
	v_mfma_f32_16x16x32_bf16 v[78:81], v[126:129], v[138:141], v[98:101]
	v_mfma_f32_16x16x32_bf16 v[90:93], v[82:85], v[158:161], v[90:93]
	v_mfma_f32_16x16x32_bf16 v[94:97], v[118:121], v[158:161], v[102:105]
	s_nop 2
	global_load_dwordx4 v[102:105], v[4:5], off offset:256
	global_load_dwordx4 v[106:109], v[0:1], off offset:256
	v_mfma_f32_16x16x32_bf16 v[98:101], v[126:129], v[158:161], v[114:117]
	s_waitcnt lgkmcnt(0)
	v_mfma_f32_16x16x32_bf16 v[34:37], v[82:85], v[162:165], v[34:37]
	global_load_dwordx4 v[82:85], v[6:7], off offset:256
	global_load_dwordx4 v[110:113], v[2:3], off offset:256
	global_load_dwordx4 v[114:117], v[22:23], off offset:256
	v_mfma_f32_16x16x32_bf16 v[46:49], v[118:121], v[162:165], v[46:49]
	global_load_dwordx4 v[118:121], v[24:25], off offset:256
	s_barrier
	v_mfma_f32_16x16x32_bf16 v[58:61], v[134:137], v[138:141], v[58:61]
	s_waitcnt vmcnt(4)
	ds_write_b128 v28, v[106:109]
	ds_write_b128 v29, v[102:105]
	s_waitcnt vmcnt(2)
	ds_write_b128 v28, v[110:113] offset:18432
	ds_write_b128 v30, v[82:85]
	s_waitcnt vmcnt(1)
	ds_write_b128 v28, v[114:117] offset:36864
	s_waitcnt vmcnt(0)
	ds_write_b128 v29, v[118:121] offset:36864
	v_mfma_f32_16x16x32_bf16 v[86:89], v[134:137], v[158:161], v[86:89]
	s_waitcnt lgkmcnt(0)
	s_barrier
	v_mfma_f32_16x16x32_bf16 v[54:57], v[126:129], v[162:165], v[54:57]
	ds_read_b128 v[82:85], v32 offset:36864
	ds_read_b128 v[102:105], v31
	ds_read_b128 v[106:109], v31 offset:64
	ds_read_b128 v[110:113], v32 offset:36928
	ds_read_b128 v[114:117], v32 offset:39168
	ds_read_b128 v[118:121], v32 offset:39232
	ds_read_b128 v[122:125], v32 offset:41472
	ds_read_b128 v[126:129], v32 offset:41536
	v_mfma_f32_16x16x32_bf16 v[66:69], v[134:137], v[162:165], v[66:69]
	ds_read_b128 v[130:133], v32 offset:43776
	ds_read_b128 v[134:137], v32 offset:43840
	s_waitcnt lgkmcnt(8)
	v_mfma_f32_16x16x32_bf16 v[50:53], v[82:85], v[102:105], v[50:53]
	s_waitcnt lgkmcnt(5)
	v_mfma_f32_16x16x32_bf16 v[62:65], v[114:117], v[102:105], v[62:65]
	s_waitcnt lgkmcnt(3)
	v_mfma_f32_16x16x32_bf16 v[70:73], v[122:125], v[102:105], v[70:73]
	s_waitcnt lgkmcnt(1)
	v_mfma_f32_16x16x32_bf16 v[38:41], v[130:133], v[102:105], v[38:41]
	ds_read_b128 v[102:105], v31 offset:2304
	ds_read_b128 v[138:141], v31 offset:2368
	s_waitcnt lgkmcnt(1)
	v_mfma_f32_16x16x32_bf16 v[42:45], v[82:85], v[102:105], v[42:45]
	v_mfma_f32_16x16x32_bf16 v[74:77], v[114:117], v[102:105], v[74:77]
	v_mfma_f32_16x16x32_bf16 v[78:81], v[122:125], v[102:105], v[78:81]
	v_mfma_f32_16x16x32_bf16 v[58:61], v[130:133], v[102:105], v[58:61]
	ds_read_b128 v[102:105], v31 offset:4608
	ds_read_b128 v[158:161], v31 offset:4672
	s_waitcnt lgkmcnt(1)
	v_mfma_f32_16x16x32_bf16 v[90:93], v[82:85], v[102:105], v[90:93]
	v_mfma_f32_16x16x32_bf16 v[94:97], v[114:117], v[102:105], v[94:97]
	v_mfma_f32_16x16x32_bf16 v[98:101], v[122:125], v[102:105], v[98:101]
	v_mfma_f32_16x16x32_bf16 v[86:89], v[130:133], v[102:105], v[86:89]
	ds_read_b128 v[102:105], v31 offset:6912
	ds_read_b128 v[162:165], v31 offset:6976
	s_waitcnt lgkmcnt(1)
	v_mfma_f32_16x16x32_bf16 v[34:37], v[82:85], v[102:105], v[34:37]
	v_mfma_f32_16x16x32_bf16 v[46:49], v[114:117], v[102:105], v[46:49]
	v_mfma_f32_16x16x32_bf16 v[54:57], v[122:125], v[102:105], v[54:57]
	v_mfma_f32_16x16x32_bf16 v[66:69], v[130:133], v[102:105], v[66:69]
	v_lshlrev_b32_e32 v130, 1, v33
	v_ashrrev_i32_e32 v131, 31, v130
	v_mfma_f32_16x16x32_bf16 v[50:53], v[110:113], v[106:109], v[50:53]
	v_mfma_f32_16x16x32_bf16 v[62:65], v[118:121], v[106:109], v[62:65]
	v_mfma_f32_16x16x32_bf16 v[70:73], v[126:129], v[106:109], v[70:73]
	v_mfma_f32_16x16x32_bf16 v[38:41], v[134:137], v[106:109], v[38:41]
	v_mfma_f32_16x16x32_bf16 v[82:85], v[110:113], v[158:161], v[90:93]
	v_mfma_f32_16x16x32_bf16 v[90:93], v[118:121], v[158:161], v[94:97]
	v_mfma_f32_16x16x32_bf16 v[94:97], v[126:129], v[158:161], v[98:101]
	s_nop 2
	global_load_dwordx4 v[98:101], v[4:5], off offset:384
	global_load_dwordx4 v[102:105], v[0:1], off offset:384
	s_nop 0
	global_load_dwordx4 v[4:7], v[6:7], off offset:384
	s_nop 0
	global_load_dwordx4 v[0:3], v[2:3], off offset:384
	s_nop 0
	global_load_dwordx4 v[106:109], v[22:23], off offset:384
	s_nop 0
	global_load_dwordx4 v[22:25], v[24:25], off offset:384
	v_mfma_f32_16x16x32_bf16 v[42:45], v[110:113], v[138:141], v[42:45]
	s_waitcnt lgkmcnt(0)
	s_barrier
	v_mfma_f32_16x16x32_bf16 v[74:77], v[118:121], v[138:141], v[74:77]
	s_waitcnt vmcnt(4)
	ds_write_b128 v28, v[102:105]
	ds_write_b128 v29, v[98:101]
	s_waitcnt vmcnt(2)
	ds_write_b128 v28, v[0:3] offset:18432
	ds_write_b128 v30, v[4:7]
	s_waitcnt vmcnt(1)
	ds_write_b128 v28, v[106:109] offset:36864
	s_waitcnt vmcnt(0)
	ds_write_b128 v29, v[22:25] offset:36864
	v_mfma_f32_16x16x32_bf16 v[34:37], v[110:113], v[162:165], v[34:37]
	s_waitcnt lgkmcnt(0)
	s_barrier
	v_mfma_f32_16x16x32_bf16 v[46:49], v[118:121], v[162:165], v[46:49]
	ds_read_b128 v[22:25], v32 offset:36864
	ds_read_b128 v[98:101], v31
	ds_read_b128 v[102:105], v31 offset:64
	ds_read_b128 v[106:109], v32 offset:36928
	ds_read_b128 v[110:113], v32 offset:39168
	ds_read_b128 v[114:117], v32 offset:39232
	ds_read_b128 v[118:121], v32 offset:41472
	ds_read_b128 v[4:7], v32 offset:41536
	ds_read_b128 v[122:125], v32 offset:43776
	ds_read_b128 v[0:3], v32 offset:43840
	v_mfma_f32_16x16x32_bf16 v[58:61], v[134:137], v[138:141], v[58:61]
	v_mfma_f32_16x16x32_bf16 v[86:89], v[134:137], v[158:161], v[86:89]
	v_mfma_f32_16x16x32_bf16 v[66:69], v[134:137], v[162:165], v[66:69]
	v_lshl_add_u64 v[134:135], v[130:131], 2, s[40:41]
	v_add_u32_e32 v130, s10, v27
	v_ashrrev_i32_e32 v130, 6, v130
	v_mfma_f32_16x16x32_bf16 v[78:81], v[126:129], v[138:141], v[78:81]
	v_mul_lo_u32 v130, v130, s5
	v_ashrrev_i32_e32 v131, 31, v130
	v_lshl_add_u64 v[138:139], v[130:131], 1, s[0:1]
	v_mfma_f32_16x16x32_bf16 v[54:57], v[126:129], v[162:165], v[54:57]
	v_mad_i64_i32 v[140:141], s[8:9], v33, s6, v[138:139]
	v_lshl_add_u64 v[140:141], v[140:141], 0, v[8:9]
	s_waitcnt lgkmcnt(8)
	v_mfma_f32_16x16x32_bf16 v[50:53], v[22:25], v[98:101], v[50:53]
	s_waitcnt lgkmcnt(5)
	v_mfma_f32_16x16x32_bf16 v[62:65], v[110:113], v[98:101], v[62:65]
	s_waitcnt lgkmcnt(3)
	v_mfma_f32_16x16x32_bf16 v[70:73], v[118:121], v[98:101], v[70:73]
	s_waitcnt lgkmcnt(1)
	v_mfma_f32_16x16x32_bf16 v[38:41], v[122:125], v[98:101], v[38:41]
	ds_read_b128 v[98:101], v31 offset:2304
	ds_read_b128 v[126:129], v31 offset:2368
	global_load_dword v136, v[134:135], off offset:4
	v_mfma_f32_16x16x32_bf16 v[50:53], v[106:109], v[102:105], v[50:53]
	s_waitcnt lgkmcnt(1)
	v_mfma_f32_16x16x32_bf16 v[42:45], v[22:25], v[98:101], v[42:45]
	v_mfma_f32_16x16x32_bf16 v[74:77], v[110:113], v[98:101], v[74:77]
	s_waitcnt vmcnt(0)
	v_mov_b32_e32 v200, v136
	s_nop 3
	v_pk_mul_f32 v[52:53], v[52:53], v[136:137] op_sel_hi:[1,0]
	v_pk_mul_f32 v[50:51], v[50:51], v[136:137] op_sel_hi:[1,0]
	v_mfma_f32_16x16x32_bf16 v[78:81], v[118:121], v[98:101], v[78:81]
	v_cvt_pk_bf16_f32 v50, v50, v51
	v_cvt_pk_bf16_f32 v51, v52, v53
	v_mfma_f32_16x16x32_bf16 v[58:61], v[122:125], v[98:101], v[58:61]
	ds_read_b128 v[98:101], v31 offset:4608
	ds_read_b128 v[130:133], v31 offset:4672
	global_store_dwordx2 v[140:141], v[50:51], off
	v_mfma_f32_16x16x32_bf16 v[50:53], v[114:117], v[102:105], v[62:65]
	v_mfma_f32_16x16x32_bf16 v[38:41], v[0:3], v[102:105], v[38:41]
	s_waitcnt lgkmcnt(2)
	v_mfma_f32_16x16x32_bf16 v[42:45], v[106:109], v[126:129], v[42:45]
	v_mov_b32_e32 v136, v200
	s_nop 3
	v_pk_mul_f32 v[52:53], v[52:53], v[136:137] op_sel_hi:[1,0]
	v_pk_mul_f32 v[50:51], v[50:51], v[136:137] op_sel_hi:[1,0]
	s_waitcnt lgkmcnt(1)
	v_mfma_f32_16x16x32_bf16 v[82:85], v[22:25], v[98:101], v[82:85]
	v_cvt_pk_bf16_f32 v50, v50, v51
	v_cvt_pk_bf16_f32 v51, v52, v53
	global_store_dwordx2 v[140:141], v[50:51], off offset:32
	v_mfma_f32_16x16x32_bf16 v[50:53], v[4:7], v[102:105], v[70:73]
	v_mov_b32_e32 v62, v200
	s_nop 6
	v_pk_mul_f32 v[52:53], v[52:53], v[62:63] op_sel_hi:[1,0]
	v_pk_mul_f32 v[50:51], v[50:51], v[62:63] op_sel_hi:[1,0]
	v_or_b32_e32 v63, 16, v33
	v_cvt_pk_bf16_f32 v50, v50, v51
	v_cvt_pk_bf16_f32 v51, v52, v53
	global_store_dwordx2 v[140:141], v[50:51], off offset:64
	v_lshlrev_b32_e32 v64, 1, v63
	v_ashrrev_i32_e32 v65, 31, v64
	v_lshl_add_u64 v[64:65], v[64:65], 2, s[40:41]
	v_mad_i64_i32 v[70:71], s[8:9], v63, s6, v[138:139]
	v_mfma_f32_16x16x32_bf16 v[50:53], v[110:113], v[98:101], v[90:93]
	v_mov_b32_e32 v62, v200
	v_pk_mul_f32 v[40:41], v[40:41], v[62:63] op_sel_hi:[1,0]
	v_pk_mul_f32 v[38:39], v[38:39], v[62:63] op_sel_hi:[1,0]
	v_lshl_add_u64 v[90:91], v[70:71], 0, v[8:9]
	v_cvt_pk_bf16_f32 v38, v38, v39
	v_cvt_pk_bf16_f32 v39, v40, v41
	global_store_dwordx2 v[140:141], v[38:39], off offset:96
	global_load_dword v62, v[64:65], off offset:4
	v_mfma_f32_16x16x32_bf16 v[38:41], v[118:121], v[98:101], v[94:97]
	s_waitcnt vmcnt(0)
	v_mov_b32_e32 v201, v62
	v_pk_mul_f32 v[44:45], v[44:45], v[62:63] op_sel_hi:[1,0]
	v_pk_mul_f32 v[42:43], v[42:43], v[62:63] op_sel_hi:[1,0]
	s_waitcnt lgkmcnt(0)
	v_mfma_f32_16x16x32_bf16 v[38:41], v[4:7], v[130:133], v[38:41]
	v_cvt_pk_bf16_f32 v42, v42, v43
	v_cvt_pk_bf16_f32 v43, v44, v45
	global_store_dwordx2 v[90:91], v[42:43], off
	v_mfma_f32_16x16x32_bf16 v[42:45], v[114:117], v[126:129], v[74:77]
	s_nop 2
	v_or_b32_e32 v75, 32, v33
	v_or_b32_e32 v33, 48, v33
	v_mov_b32_e32 v62, v201
	s_nop 1
	v_pk_mul_f32 v[44:45], v[44:45], v[62:63] op_sel_hi:[1,0]
	v_pk_mul_f32 v[42:43], v[42:43], v[62:63] op_sel_hi:[1,0]
	s_nop 0
	v_cvt_pk_bf16_f32 v42, v42, v43
	v_cvt_pk_bf16_f32 v43, v44, v45
	global_store_dwordx2 v[90:91], v[42:43], off offset:32
	v_mfma_f32_16x16x32_bf16 v[42:45], v[4:7], v[126:129], v[78:81]
	v_mov_b32_e32 v62, v201
	s_nop 6
	v_pk_mul_f32 v[44:45], v[44:45], v[62:63] op_sel_hi:[1,0]
	v_pk_mul_f32 v[42:43], v[42:43], v[62:63] op_sel_hi:[1,0]
	s_nop 0
	v_cvt_pk_bf16_f32 v42, v42, v43
	v_cvt_pk_bf16_f32 v43, v44, v45
	global_store_dwordx2 v[90:91], v[42:43], off offset:64
	ds_read_b128 v[62:65], v31 offset:6912
	ds_read_b128 v[70:73], v31 offset:6976
	s_waitcnt lgkmcnt(1)
	v_mfma_f32_16x16x32_bf16 v[22:25], v[22:25], v[62:65], v[34:37]
	s_nop 2
	v_lshlrev_b32_e32 v34, 1, v75
	v_ashrrev_i32_e32 v35, 31, v34
	v_lshl_add_u64 v[76:77], v[34:35], 2, s[40:41]
	v_mfma_f32_16x16x32_bf16 v[34:37], v[0:3], v[126:129], v[58:61]
	v_mfma_f32_16x16x32_bf16 v[42:45], v[122:125], v[98:101], v[86:89]
	v_mfma_f32_16x16x32_bf16 v[42:45], v[0:3], v[130:133], v[42:45]
	v_mov_b32_e32 v74, v201
	s_nop 4
	v_pk_mul_f32 v[36:37], v[36:37], v[74:75] op_sel_hi:[1,0]
	v_pk_mul_f32 v[34:35], v[34:35], v[74:75] op_sel_hi:[1,0]
	s_waitcnt lgkmcnt(0)
	v_mfma_f32_16x16x32_bf16 v[22:25], v[106:109], v[70:73], v[22:25]
	v_cvt_pk_bf16_f32 v34, v34, v35
	v_cvt_pk_bf16_f32 v35, v36, v37
	global_store_dwordx2 v[90:91], v[34:35], off offset:96
	global_load_dword v58, v[76:77], off offset:4
	v_mfma_f32_16x16x32_bf16 v[34:37], v[110:113], v[62:65], v[46:49]
	s_nop 2
	v_mad_i64_i32 v[46:47], s[8:9], v75, s6, v[138:139]
	v_lshl_add_u64 v[60:61], v[46:47], 0, v[8:9]
	v_mfma_f32_16x16x32_bf16 v[46:49], v[106:109], v[130:133], v[82:85]
	s_waitcnt vmcnt(0)
	v_mov_b32_e32 v202, v58
	s_nop 6
	v_pk_mul_f32 v[48:49], v[48:49], v[58:59] op_sel_hi:[1,0]
	v_pk_mul_f32 v[46:47], v[46:47], v[58:59] op_sel_hi:[1,0]
	s_nop 0
	v_cvt_pk_bf16_f32 v46, v46, v47
	v_cvt_pk_bf16_f32 v47, v48, v49
	global_store_dwordx2 v[60:61], v[46:47], off
	v_mfma_f32_16x16x32_bf16 v[46:49], v[114:117], v[130:133], v[50:53]
	s_nop 2
	v_mad_i64_i32 v[50:51], s[8:9], v33, s6, v[138:139]
	v_lshl_add_u64 v[50:51], v[50:51], 0, v[8:9]
	v_mov_b32_e32 v58, v202
	s_nop 1
	v_pk_mul_f32 v[48:49], v[48:49], v[58:59] op_sel_hi:[1,0]
	v_pk_mul_f32 v[46:47], v[46:47], v[58:59] op_sel_hi:[1,0]
	s_nop 0
	v_cvt_pk_bf16_f32 v46, v46, v47
	v_cvt_pk_bf16_f32 v47, v48, v49
	global_store_dwordx2 v[60:61], v[46:47], off offset:32
	v_lshlrev_b32_e32 v48, 1, v33
	v_ashrrev_i32_e32 v49, 31, v48
	v_lshl_add_u64 v[48:49], v[48:49], 2, s[40:41]
	v_mov_b32_e32 v46, v202
	v_pk_mul_f32 v[40:41], v[40:41], v[46:47] op_sel_hi:[1,0]
	v_pk_mul_f32 v[38:39], v[38:39], v[46:47] op_sel_hi:[1,0]
	s_nop 0
	v_cvt_pk_bf16_f32 v38, v38, v39
	v_cvt_pk_bf16_f32 v39, v40, v41
	global_store_dwordx2 v[60:61], v[38:39], off offset:64
	v_mfma_f32_16x16x32_bf16 v[38:41], v[118:121], v[62:65], v[54:57]
	v_mov_b32_e32 v46, v202
	v_pk_mul_f32 v[44:45], v[44:45], v[46:47] op_sel_hi:[1,0]
	v_pk_mul_f32 v[42:43], v[42:43], v[46:47] op_sel_hi:[1,0]
	v_mfma_f32_16x16x32_bf16 v[4:7], v[4:7], v[70:73], v[38:41]
	v_cvt_pk_bf16_f32 v42, v42, v43
	v_cvt_pk_bf16_f32 v43, v44, v45
	global_store_dwordx2 v[60:61], v[42:43], off offset:96
	global_load_dword v46, v[48:49], off offset:4
	v_mfma_f32_16x16x32_bf16 v[42:45], v[122:125], v[62:65], v[66:69]
	s_waitcnt vmcnt(0)
	v_mov_b32_e32 v203, v46
	v_pk_mul_f32 v[24:25], v[24:25], v[46:47] op_sel_hi:[1,0]
	v_pk_mul_f32 v[22:23], v[22:23], v[46:47] op_sel_hi:[1,0]
	v_mfma_f32_16x16x32_bf16 v[0:3], v[0:3], v[70:73], v[42:45]
	v_cvt_pk_bf16_f32 v22, v22, v23
	v_cvt_pk_bf16_f32 v23, v24, v25
	global_store_dwordx2 v[50:51], v[22:23], off
	v_mfma_f32_16x16x32_bf16 v[22:25], v[114:117], v[70:73], v[34:37]
	v_mov_b32_e32 v46, v203
	s_nop 6
	v_pk_mul_f32 v[24:25], v[24:25], v[46:47] op_sel_hi:[1,0]
	v_pk_mul_f32 v[22:23], v[22:23], v[46:47] op_sel_hi:[1,0]
	s_nop 0
	v_cvt_pk_bf16_f32 v22, v22, v23
	v_cvt_pk_bf16_f32 v23, v24, v25
	global_store_dwordx2 v[50:51], v[22:23], off offset:32
	v_mov_b32_e32 v22, v203
	v_pk_mul_f32 v[6:7], v[6:7], v[22:23] op_sel_hi:[1,0]
	v_pk_mul_f32 v[4:5], v[4:5], v[22:23] op_sel_hi:[1,0]
	s_nop 0
	v_cvt_pk_bf16_f32 v4, v4, v5
	v_cvt_pk_bf16_f32 v5, v6, v7
	global_store_dwordx2 v[50:51], v[4:5], off offset:64
	v_mov_b32_e32 v4, v203
	v_pk_mul_f32 v[2:3], v[2:3], v[4:5] op_sel_hi:[1,0]
	v_pk_mul_f32 v[0:1], v[0:1], v[4:5] op_sel_hi:[1,0]
	s_nop 0
	v_cvt_pk_bf16_f32 v0, v0, v1
	v_cvt_pk_bf16_f32 v1, v2, v3
	global_store_dwordx2 v[50:51], v[0:1], off offset:96
	s_cbranch_scc1 .LBB0_2610

.LBB0_2631:
	v_lshl_add_u32 v171, s44, 8, v138
	v_mul_hi_i32 v136, v171, s31
	v_lshrrev_b32_e32 v137, 31, v136
	v_ashrrev_i32_e32 v136, 11, v136
	v_add_u32_e32 v136, v136, v137
	v_mad_i32_i24 v172, v136, s36, v171
	v_lshlrev_b32_e32 v180, 10, v136
	v_lshlrev_b32_e32 v136, 1, v171
	v_ashrrev_i32_e32 v137, 31, v136
	v_lshl_add_u64 v[136:137], v[136:137], 2, s[40:41]
	global_load_dword v174, v[136:137], off offset:4
	v_lshl_or_b32 v170, s66, 8, v140
	v_ashrrev_i32_e32 v173, 31, v172
	v_or_b32_e32 v181, 16, v180
	v_readlane_b32 s82, v255, 11
	v_readlane_b32 s70, v255, 21
	v_readlane_b32 s83, v255, 12
	v_readlane_b32 s71, v255, 22
	s_waitcnt vmcnt(0)
	v_mov_b32_e32 v182, v174
	v_pk_mul_f32 v[176:177], v[126:127], v[174:175] op_sel_hi:[1,0]
	v_pk_mul_f32 v[174:175], v[124:125], v[174:175] op_sel_hi:[1,0]
	v_add_u32_e32 v126, v180, v170
	v_mov_b64_e32 v[124:125], s[12:13]
	v_mad_i64_i32 v[178:179], s[4:5], v126, s37, v[124:125]
	v_lshlrev_b64 v[126:127], 1, v[172:173]
	v_lshl_add_u64 v[172:173], v[178:179], 0, v[126:127]
	v_cvt_pk_bf16_f32 v174, v174, s0
	global_store_short v[172:173], v174, off
	v_add_co_u32_e32 v174, vcc, s91, v172
	v_cvt_pk_bf16_f32 v178, v175, s0
	s_nop 0
	v_addc_co_u32_e32 v175, vcc, 0, v173, vcc
	global_store_short v[174:175], v178, off offset:512
	v_add_co_u32_e32 v174, vcc, s76, v172
	v_cvt_pk_bf16_f32 v176, v176, s0
	s_nop 0
	v_addc_co_u32_e32 v175, vcc, 0, v173, vcc
	v_add_co_u32_e32 v172, vcc, s34, v172
	global_store_short v[174:175], v176, off offset:1024
	v_cvt_pk_bf16_f32 v174, v177, s0
	v_addc_co_u32_e32 v173, vcc, 0, v173, vcc
	global_store_short v[172:173], v174, off offset:1536
	v_mov_b32_e32 v172, v182
	v_pk_mul_f32 v[122:123], v[122:123], v[172:173] op_sel_hi:[1,0]
	v_pk_mul_f32 v[120:121], v[120:121], v[172:173] op_sel_hi:[1,0]
	v_add_u32_e32 v172, v181, v170
	v_mad_i64_i32 v[172:173], s[4:5], v172, s37, v[124:125]
	v_lshl_add_u64 v[172:173], v[172:173], 0, v[126:127]
	v_cvt_pk_bf16_f32 v120, v120, s0
	global_store_short v[172:173], v120, off
	v_add_co_u32_e32 v120, vcc, s91, v172
	v_cvt_pk_bf16_f32 v174, v121, s0
	s_nop 0
	v_addc_co_u32_e32 v121, vcc, 0, v173, vcc
	global_store_short v[120:121], v174, off offset:512
	v_add_co_u32_e32 v120, vcc, s76, v172
	v_cvt_pk_bf16_f32 v122, v122, s0
	s_nop 0
	v_addc_co_u32_e32 v121, vcc, 0, v173, vcc
	global_store_short v[120:121], v122, off offset:1024
	v_add_co_u32_e32 v120, vcc, s34, v172
	v_cvt_pk_bf16_f32 v122, v123, s0
	s_nop 0
	v_addc_co_u32_e32 v121, vcc, 0, v173, vcc
	global_store_short v[120:121], v122, off offset:1536
	v_or_b32_e32 v120, 0x80, v170
	v_add_u32_e32 v121, v180, v120
	v_mov_b32_e32 v122, v182
	v_pk_mul_f32 v[118:119], v[118:119], v[122:123] op_sel_hi:[1,0]
	v_pk_mul_f32 v[116:117], v[116:117], v[122:123] op_sel_hi:[1,0]
	v_mad_i64_i32 v[122:123], s[4:5], v121, s37, v[124:125]
	v_lshl_add_u64 v[122:123], v[122:123], 0, v[126:127]
	v_cvt_pk_bf16_f32 v116, v116, s0
	global_store_short v[122:123], v116, off
	v_add_co_u32_e32 v116, vcc, s91, v122
	v_cvt_pk_bf16_f32 v121, v117, s0
	s_nop 0
	v_addc_co_u32_e32 v117, vcc, 0, v123, vcc
	global_store_short v[116:117], v121, off offset:512
	v_add_co_u32_e32 v116, vcc, s76, v122
	v_cvt_pk_bf16_f32 v118, v118, s0
	s_nop 0
	v_addc_co_u32_e32 v117, vcc, 0, v123, vcc
	global_store_short v[116:117], v118, off offset:1024
	v_add_co_u32_e32 v116, vcc, s34, v122
	v_cvt_pk_bf16_f32 v118, v119, s0
	s_nop 0
	v_addc_co_u32_e32 v117, vcc, 0, v123, vcc
	global_store_short v[116:117], v118, off offset:1536
	v_mov_b32_e32 v116, v182
	v_pk_mul_f32 v[114:115], v[114:115], v[116:117] op_sel_hi:[1,0]
	v_pk_mul_f32 v[112:113], v[112:113], v[116:117] op_sel_hi:[1,0]
	v_add_u32_e32 v116, v181, v120
	v_mad_i64_i32 v[116:117], s[4:5], v116, s37, v[124:125]
	v_lshl_add_u64 v[116:117], v[116:117], 0, v[126:127]
	v_cvt_pk_bf16_f32 v112, v112, s0
	global_store_short v[116:117], v112, off
	v_add_co_u32_e32 v112, vcc, s91, v116
	v_cvt_pk_bf16_f32 v118, v113, s0
	s_nop 0
	v_addc_co_u32_e32 v113, vcc, 0, v117, vcc
	global_store_short v[112:113], v118, off offset:512
	v_add_co_u32_e32 v112, vcc, s76, v116
	v_cvt_pk_bf16_f32 v114, v114, s0
	s_nop 0
	v_addc_co_u32_e32 v113, vcc, 0, v117, vcc
	global_store_short v[112:113], v114, off offset:1024
	v_add_co_u32_e32 v112, vcc, s34, v116
	v_cvt_pk_bf16_f32 v114, v115, s0
	s_nop 0
	v_addc_co_u32_e32 v113, vcc, 0, v117, vcc
	global_store_short v[112:113], v114, off offset:1536
	v_or_b32_e32 v112, 16, v171
	v_mul_hi_i32 v113, v112, s31
	v_lshrrev_b32_e32 v114, 31, v113
	v_ashrrev_i32_e32 v113, 11, v113
	v_add_u32_e32 v113, v113, v114
	v_mad_i32_i24 v114, v113, s36, v112
	v_lshlrev_b32_e32 v112, 1, v112
	v_lshlrev_b32_e32 v121, 10, v113
	v_ashrrev_i32_e32 v113, 31, v112
	v_lshl_add_u64 v[112:113], v[112:113], 2, s[40:41]
	global_load_dword v116, v[112:113], off offset:4
	v_ashrrev_i32_e32 v115, 31, v114
	v_or_b32_e32 v122, 16, v121
	s_waitcnt vmcnt(0)
	v_mov_b32_e32 v183, v116
	v_pk_mul_f32 v[110:111], v[110:111], v[116:117] op_sel_hi:[1,0]
	v_pk_mul_f32 v[116:117], v[108:109], v[116:117] op_sel_hi:[1,0]
	v_add_u32_e32 v108, v121, v170
	v_mad_i64_i32 v[118:119], s[4:5], v108, s37, v[124:125]
	v_lshlrev_b64 v[108:109], 1, v[114:115]
	v_lshl_add_u64 v[114:115], v[118:119], 0, v[108:109]
	v_cvt_pk_bf16_f32 v116, v116, s0
	global_store_short v[114:115], v116, off
	v_add_co_u32_e32 v116, vcc, s91, v114
	v_cvt_pk_bf16_f32 v118, v117, s0
	s_nop 0
	v_addc_co_u32_e32 v117, vcc, 0, v115, vcc
	global_store_short v[116:117], v118, off offset:512
	v_add_co_u32_e32 v116, vcc, s76, v114
	v_cvt_pk_bf16_f32 v110, v110, s0
	s_nop 0
	v_addc_co_u32_e32 v117, vcc, 0, v115, vcc
	global_store_short v[116:117], v110, off offset:1024
	v_add_co_u32_e32 v110, vcc, s34, v114
	v_cvt_pk_bf16_f32 v116, v111, s0
	s_nop 0
	v_addc_co_u32_e32 v111, vcc, 0, v115, vcc
	global_store_short v[110:111], v116, off offset:1536
	v_mov_b32_e32 v110, v183
	v_pk_mul_f32 v[106:107], v[106:107], v[110:111] op_sel_hi:[1,0]
	v_pk_mul_f32 v[104:105], v[104:105], v[110:111] op_sel_hi:[1,0]
	v_add_u32_e32 v110, v122, v170
	v_mad_i64_i32 v[110:111], s[4:5], v110, s37, v[124:125]
	v_lshl_add_u64 v[110:111], v[110:111], 0, v[108:109]
	v_cvt_pk_bf16_f32 v104, v104, s0
	global_store_short v[110:111], v104, off
	v_add_co_u32_e32 v104, vcc, s91, v110
	v_cvt_pk_bf16_f32 v114, v105, s0
	s_nop 0
	v_addc_co_u32_e32 v105, vcc, 0, v111, vcc
	global_store_short v[104:105], v114, off offset:512
	v_add_co_u32_e32 v104, vcc, s76, v110
	v_cvt_pk_bf16_f32 v106, v106, s0
	s_nop 0
	v_addc_co_u32_e32 v105, vcc, 0, v111, vcc
	global_store_short v[104:105], v106, off offset:1024
	v_add_co_u32_e32 v104, vcc, s34, v110
	v_cvt_pk_bf16_f32 v106, v107, s0
	s_nop 0
	v_addc_co_u32_e32 v105, vcc, 0, v111, vcc
	global_store_short v[104:105], v106, off offset:1536
	v_mov_b32_e32 v104, v183
	v_pk_mul_f32 v[102:103], v[102:103], v[104:105] op_sel_hi:[1,0]
	v_pk_mul_f32 v[100:101], v[100:101], v[104:105] op_sel_hi:[1,0]
	v_add_u32_e32 v104, v121, v120
	v_mad_i64_i32 v[104:105], s[4:5], v104, s37, v[124:125]
	v_lshl_add_u64 v[104:105], v[104:105], 0, v[108:109]
	v_cvt_pk_bf16_f32 v100, v100, s0
	global_store_short v[104:105], v100, off
	v_add_co_u32_e32 v100, vcc, s91, v104
	v_cvt_pk_bf16_f32 v106, v101, s0
	s_nop 0
	v_addc_co_u32_e32 v101, vcc, 0, v105, vcc
	global_store_short v[100:101], v106, off offset:512
	v_add_co_u32_e32 v100, vcc, s76, v104
	v_cvt_pk_bf16_f32 v102, v102, s0
	s_nop 0
	v_addc_co_u32_e32 v101, vcc, 0, v105, vcc
	global_store_short v[100:101], v102, off offset:1024
	v_add_co_u32_e32 v100, vcc, s34, v104
	v_cvt_pk_bf16_f32 v102, v103, s0
	s_nop 0
	v_addc_co_u32_e32 v101, vcc, 0, v105, vcc
	global_store_short v[100:101], v102, off offset:1536
	v_mov_b32_e32 v100, v183
	v_pk_mul_f32 v[98:99], v[98:99], v[100:101] op_sel_hi:[1,0]
	v_pk_mul_f32 v[96:97], v[96:97], v[100:101] op_sel_hi:[1,0]
	v_add_u32_e32 v100, v122, v120
	v_mad_i64_i32 v[100:101], s[4:5], v100, s37, v[124:125]
	v_lshl_add_u64 v[100:101], v[100:101], 0, v[108:109]
	v_cvt_pk_bf16_f32 v96, v96, s0
	global_store_short v[100:101], v96, off
	v_add_co_u32_e32 v96, vcc, s91, v100
	v_cvt_pk_bf16_f32 v102, v97, s0
	s_nop 0
	v_addc_co_u32_e32 v97, vcc, 0, v101, vcc
	global_store_short v[96:97], v102, off offset:512
	v_add_co_u32_e32 v96, vcc, s76, v100
	v_cvt_pk_bf16_f32 v98, v98, s0
	s_nop 0
	v_addc_co_u32_e32 v97, vcc, 0, v101, vcc
	global_store_short v[96:97], v98, off offset:1024
	v_add_co_u32_e32 v96, vcc, s34, v100
	v_cvt_pk_bf16_f32 v98, v99, s0
	s_nop 0
	v_addc_co_u32_e32 v97, vcc, 0, v101, vcc
	global_store_short v[96:97], v98, off offset:1536
	v_or_b32_e32 v96, 32, v171
	v_mul_hi_i32 v97, v96, s31
	v_lshrrev_b32_e32 v98, 31, v97
	v_ashrrev_i32_e32 v97, 11, v97
	v_add_u32_e32 v97, v97, v98
	v_mad_i32_i24 v98, v97, s36, v96
	v_lshlrev_b32_e32 v96, 1, v96
	v_lshlrev_b32_e32 v104, 10, v97
	v_ashrrev_i32_e32 v97, 31, v96
	v_lshl_add_u64 v[96:97], v[96:97], 2, s[40:41]
	global_load_dword v100, v[96:97], off offset:4
	v_ashrrev_i32_e32 v99, 31, v98
	v_or_b32_e32 v105, 16, v104
	s_waitcnt vmcnt(0)
	v_mov_b32_e32 v184, v100
	v_pk_mul_f32 v[94:95], v[94:95], v[100:101] op_sel_hi:[1,0]
	v_pk_mul_f32 v[100:101], v[92:93], v[100:101] op_sel_hi:[1,0]
	v_add_u32_e32 v92, v104, v170
	v_mad_i64_i32 v[102:103], s[4:5], v92, s37, v[124:125]
	v_lshlrev_b64 v[92:93], 1, v[98:99]
	v_lshl_add_u64 v[98:99], v[102:103], 0, v[92:93]
	v_cvt_pk_bf16_f32 v100, v100, s0
	global_store_short v[98:99], v100, off
	v_add_co_u32_e32 v100, vcc, s91, v98
	v_cvt_pk_bf16_f32 v102, v101, s0
	s_nop 0
	v_addc_co_u32_e32 v101, vcc, 0, v99, vcc
	global_store_short v[100:101], v102, off offset:512
	v_add_co_u32_e32 v100, vcc, s76, v98
	v_cvt_pk_bf16_f32 v94, v94, s0
	s_nop 0
	v_addc_co_u32_e32 v101, vcc, 0, v99, vcc
	global_store_short v[100:101], v94, off offset:1024
	v_add_co_u32_e32 v94, vcc, s34, v98
	v_cvt_pk_bf16_f32 v100, v95, s0
	s_nop 0
	v_addc_co_u32_e32 v95, vcc, 0, v99, vcc
	global_store_short v[94:95], v100, off offset:1536
	v_mov_b32_e32 v94, v184
	v_pk_mul_f32 v[90:91], v[90:91], v[94:95] op_sel_hi:[1,0]
	v_pk_mul_f32 v[88:89], v[88:89], v[94:95] op_sel_hi:[1,0]
	v_add_u32_e32 v94, v105, v170
	v_mad_i64_i32 v[94:95], s[4:5], v94, s37, v[124:125]
	v_lshl_add_u64 v[94:95], v[94:95], 0, v[92:93]
	v_cvt_pk_bf16_f32 v88, v88, s0
	global_store_short v[94:95], v88, off
	v_add_co_u32_e32 v88, vcc, s91, v94
	v_cvt_pk_bf16_f32 v98, v89, s0
	s_nop 0
	v_addc_co_u32_e32 v89, vcc, 0, v95, vcc
	global_store_short v[88:89], v98, off offset:512
	v_add_co_u32_e32 v88, vcc, s76, v94
	v_cvt_pk_bf16_f32 v90, v90, s0
	s_nop 0
	v_addc_co_u32_e32 v89, vcc, 0, v95, vcc
	global_store_short v[88:89], v90, off offset:1024
	v_add_co_u32_e32 v88, vcc, s34, v94
	v_cvt_pk_bf16_f32 v90, v91, s0
	s_nop 0
	v_addc_co_u32_e32 v89, vcc, 0, v95, vcc
	global_store_short v[88:89], v90, off offset:1536
	v_mov_b32_e32 v88, v184
	v_pk_mul_f32 v[86:87], v[86:87], v[88:89] op_sel_hi:[1,0]
	v_pk_mul_f32 v[84:85], v[84:85], v[88:89] op_sel_hi:[1,0]
	v_add_u32_e32 v88, v104, v120
	v_mad_i64_i32 v[88:89], s[4:5], v88, s37, v[124:125]
	v_lshl_add_u64 v[88:89], v[88:89], 0, v[92:93]
	v_cvt_pk_bf16_f32 v84, v84, s0
	global_store_short v[88:89], v84, off
	v_add_co_u32_e32 v84, vcc, s91, v88
	v_cvt_pk_bf16_f32 v90, v85, s0
	s_nop 0
	v_addc_co_u32_e32 v85, vcc, 0, v89, vcc
	global_store_short v[84:85], v90, off offset:512
	v_add_co_u32_e32 v84, vcc, s76, v88
	v_cvt_pk_bf16_f32 v86, v86, s0
	s_nop 0
	v_addc_co_u32_e32 v85, vcc, 0, v89, vcc
	global_store_short v[84:85], v86, off offset:1024
	v_add_co_u32_e32 v84, vcc, s34, v88
	v_cvt_pk_bf16_f32 v86, v87, s0
	s_nop 0
	v_addc_co_u32_e32 v85, vcc, 0, v89, vcc
	global_store_short v[84:85], v86, off offset:1536
	v_mov_b32_e32 v84, v184
	v_pk_mul_f32 v[82:83], v[82:83], v[84:85] op_sel_hi:[1,0]
	v_pk_mul_f32 v[80:81], v[80:81], v[84:85] op_sel_hi:[1,0]
	v_add_u32_e32 v84, v105, v120
	v_mad_i64_i32 v[84:85], s[4:5], v84, s37, v[124:125]
	v_lshl_add_u64 v[84:85], v[84:85], 0, v[92:93]
	v_cvt_pk_bf16_f32 v80, v80, s0
	global_store_short v[84:85], v80, off
	v_add_co_u32_e32 v80, vcc, s91, v84
	v_cvt_pk_bf16_f32 v86, v81, s0
	s_nop 0
	v_addc_co_u32_e32 v81, vcc, 0, v85, vcc
	global_store_short v[80:81], v86, off offset:512
	v_add_co_u32_e32 v80, vcc, s76, v84
	v_cvt_pk_bf16_f32 v82, v82, s0
	s_nop 0
	v_addc_co_u32_e32 v81, vcc, 0, v85, vcc
	global_store_short v[80:81], v82, off offset:1024
	v_add_co_u32_e32 v80, vcc, s34, v84
	v_cvt_pk_bf16_f32 v82, v83, s0
	s_nop 0
	v_addc_co_u32_e32 v81, vcc, 0, v85, vcc
	global_store_short v[80:81], v82, off offset:1536
	v_or_b32_e32 v80, 48, v171
	v_mul_hi_i32 v81, v80, s31
	v_lshrrev_b32_e32 v82, 31, v81
	v_ashrrev_i32_e32 v81, 11, v81
	v_add_u32_e32 v81, v81, v82
	v_mad_i32_i24 v82, v81, s36, v80
	v_lshlrev_b32_e32 v80, 1, v80
	v_lshlrev_b32_e32 v88, 10, v81
	v_ashrrev_i32_e32 v81, 31, v80
	v_lshl_add_u64 v[80:81], v[80:81], 2, s[40:41]
	global_load_dword v84, v[80:81], off offset:4
	v_ashrrev_i32_e32 v83, 31, v82
	v_or_b32_e32 v89, 16, v88
	s_waitcnt vmcnt(0)
	v_mov_b32_e32 v185, v84
	v_pk_mul_f32 v[78:79], v[78:79], v[84:85] op_sel_hi:[1,0]
	v_pk_mul_f32 v[84:85], v[76:77], v[84:85] op_sel_hi:[1,0]
	v_add_u32_e32 v76, v88, v170
	v_mad_i64_i32 v[86:87], s[4:5], v76, s37, v[124:125]
	v_lshlrev_b64 v[76:77], 1, v[82:83]
	v_lshl_add_u64 v[82:83], v[86:87], 0, v[76:77]
	v_cvt_pk_bf16_f32 v84, v84, s0
	global_store_short v[82:83], v84, off
	v_add_co_u32_e32 v84, vcc, s91, v82
	v_cvt_pk_bf16_f32 v86, v85, s0
	s_nop 0
	v_addc_co_u32_e32 v85, vcc, 0, v83, vcc
	global_store_short v[84:85], v86, off offset:512
	v_add_co_u32_e32 v84, vcc, s76, v82
	v_cvt_pk_bf16_f32 v78, v78, s0
	s_nop 0
	v_addc_co_u32_e32 v85, vcc, 0, v83, vcc
	global_store_short v[84:85], v78, off offset:1024
	v_add_co_u32_e32 v78, vcc, s34, v82
	v_cvt_pk_bf16_f32 v84, v79, s0
	s_nop 0
	v_addc_co_u32_e32 v79, vcc, 0, v83, vcc
	global_store_short v[78:79], v84, off offset:1536
	v_mov_b32_e32 v78, v185
	v_pk_mul_f32 v[74:75], v[74:75], v[78:79] op_sel_hi:[1,0]
	v_pk_mul_f32 v[72:73], v[72:73], v[78:79] op_sel_hi:[1,0]
	v_add_u32_e32 v78, v89, v170
	v_mad_i64_i32 v[78:79], s[4:5], v78, s37, v[124:125]
	v_lshl_add_u64 v[78:79], v[78:79], 0, v[76:77]
	v_cvt_pk_bf16_f32 v72, v72, s0
	global_store_short v[78:79], v72, off
	v_add_co_u32_e32 v72, vcc, s91, v78
	v_cvt_pk_bf16_f32 v82, v73, s0
	s_nop 0
	v_addc_co_u32_e32 v73, vcc, 0, v79, vcc
	global_store_short v[72:73], v82, off offset:512
	v_add_co_u32_e32 v72, vcc, s76, v78
	v_cvt_pk_bf16_f32 v74, v74, s0
	s_nop 0
	v_addc_co_u32_e32 v73, vcc, 0, v79, vcc
	global_store_short v[72:73], v74, off offset:1024
	v_add_co_u32_e32 v72, vcc, s34, v78
	v_cvt_pk_bf16_f32 v74, v75, s0
	s_nop 0
	v_addc_co_u32_e32 v73, vcc, 0, v79, vcc
	global_store_short v[72:73], v74, off offset:1536
	v_mov_b32_e32 v72, v185
	v_pk_mul_f32 v[70:71], v[70:71], v[72:73] op_sel_hi:[1,0]
	v_pk_mul_f32 v[68:69], v[68:69], v[72:73] op_sel_hi:[1,0]
	v_add_u32_e32 v72, v88, v120
	v_mad_i64_i32 v[72:73], s[4:5], v72, s37, v[124:125]
	v_lshl_add_u64 v[72:73], v[72:73], 0, v[76:77]
	v_cvt_pk_bf16_f32 v68, v68, s0
	global_store_short v[72:73], v68, off
	v_add_co_u32_e32 v68, vcc, s91, v72
	v_cvt_pk_bf16_f32 v74, v69, s0
	s_nop 0
	v_addc_co_u32_e32 v69, vcc, 0, v73, vcc
	global_store_short v[68:69], v74, off offset:512
	v_add_co_u32_e32 v68, vcc, s76, v72
	v_cvt_pk_bf16_f32 v70, v70, s0
	s_nop 0
	v_addc_co_u32_e32 v69, vcc, 0, v73, vcc
	global_store_short v[68:69], v70, off offset:1024
	v_add_co_u32_e32 v68, vcc, s34, v72
	v_cvt_pk_bf16_f32 v70, v71, s0
	s_nop 0
	v_addc_co_u32_e32 v69, vcc, 0, v73, vcc
	global_store_short v[68:69], v70, off offset:1536
	v_mov_b32_e32 v68, v185
	v_pk_mul_f32 v[66:67], v[66:67], v[68:69] op_sel_hi:[1,0]
	v_pk_mul_f32 v[64:65], v[64:65], v[68:69] op_sel_hi:[1,0]
	v_add_u32_e32 v68, v89, v120
	v_mad_i64_i32 v[68:69], s[4:5], v68, s37, v[124:125]
	v_lshl_add_u64 v[68:69], v[68:69], 0, v[76:77]
	v_cvt_pk_bf16_f32 v64, v64, s0
	global_store_short v[68:69], v64, off
	v_add_co_u32_e32 v64, vcc, s91, v68
	v_cvt_pk_bf16_f32 v70, v65, s0
	s_nop 0
	v_addc_co_u32_e32 v65, vcc, 0, v69, vcc
	global_store_short v[64:65], v70, off offset:512
	v_add_co_u32_e32 v64, vcc, s76, v68
	v_cvt_pk_bf16_f32 v66, v66, s0
	s_nop 0
	v_addc_co_u32_e32 v65, vcc, 0, v69, vcc
	global_store_short v[64:65], v66, off offset:1024
	v_add_co_u32_e32 v64, vcc, s34, v68
	v_cvt_pk_bf16_f32 v66, v67, s0
	s_nop 0
	v_addc_co_u32_e32 v65, vcc, 0, v69, vcc
	global_store_short v[64:65], v66, off offset:1536
	v_add_u32_e32 v64, 0x80, v171
	v_mul_hi_i32 v65, v64, s31
	v_lshrrev_b32_e32 v66, 31, v65
	v_ashrrev_i32_e32 v65, 11, v65
	v_add_u32_e32 v65, v65, v66
	v_mad_i32_i24 v66, v65, s36, v64
	v_lshlrev_b32_e32 v64, 1, v64
	v_lshlrev_b32_e32 v72, 10, v65
	v_ashrrev_i32_e32 v65, 31, v64
	v_lshl_add_u64 v[64:65], v[64:65], 2, s[40:41]
	global_load_dword v68, v[64:65], off offset:4
	v_ashrrev_i32_e32 v67, 31, v66
	v_or_b32_e32 v73, 16, v72
	s_waitcnt vmcnt(0)
	v_mov_b32_e32 v186, v68
	v_pk_mul_f32 v[62:63], v[62:63], v[68:69] op_sel_hi:[1,0]
	v_pk_mul_f32 v[68:69], v[60:61], v[68:69] op_sel_hi:[1,0]
	v_add_u32_e32 v60, v72, v170
	v_mad_i64_i32 v[70:71], s[4:5], v60, s37, v[124:125]
	v_lshlrev_b64 v[60:61], 1, v[66:67]
	v_lshl_add_u64 v[66:67], v[70:71], 0, v[60:61]
	v_cvt_pk_bf16_f32 v68, v68, s0
	global_store_short v[66:67], v68, off
	v_add_co_u32_e32 v68, vcc, s91, v66
	v_cvt_pk_bf16_f32 v70, v69, s0
	s_nop 0
	v_addc_co_u32_e32 v69, vcc, 0, v67, vcc
	global_store_short v[68:69], v70, off offset:512
	v_add_co_u32_e32 v68, vcc, s76, v66
	v_cvt_pk_bf16_f32 v62, v62, s0
	s_nop 0
	v_addc_co_u32_e32 v69, vcc, 0, v67, vcc
	global_store_short v[68:69], v62, off offset:1024
	v_add_co_u32_e32 v62, vcc, s34, v66
	v_cvt_pk_bf16_f32 v68, v63, s0
	s_nop 0
	v_addc_co_u32_e32 v63, vcc, 0, v67, vcc
	global_store_short v[62:63], v68, off offset:1536
	v_mov_b32_e32 v62, v186
	v_pk_mul_f32 v[58:59], v[58:59], v[62:63] op_sel_hi:[1,0]
	v_pk_mul_f32 v[56:57], v[56:57], v[62:63] op_sel_hi:[1,0]
	v_add_u32_e32 v62, v73, v170
	v_mad_i64_i32 v[62:63], s[4:5], v62, s37, v[124:125]
	v_lshl_add_u64 v[62:63], v[62:63], 0, v[60:61]
	v_cvt_pk_bf16_f32 v56, v56, s0
	global_store_short v[62:63], v56, off
	v_add_co_u32_e32 v56, vcc, s91, v62
	v_cvt_pk_bf16_f32 v66, v57, s0
	s_nop 0
	v_addc_co_u32_e32 v57, vcc, 0, v63, vcc
	global_store_short v[56:57], v66, off offset:512
	v_add_co_u32_e32 v56, vcc, s76, v62
	v_cvt_pk_bf16_f32 v58, v58, s0
	s_nop 0
	v_addc_co_u32_e32 v57, vcc, 0, v63, vcc
	global_store_short v[56:57], v58, off offset:1024
	v_add_co_u32_e32 v56, vcc, s34, v62
	v_cvt_pk_bf16_f32 v58, v59, s0
	s_nop 0
	v_addc_co_u32_e32 v57, vcc, 0, v63, vcc
	global_store_short v[56:57], v58, off offset:1536
	v_mov_b32_e32 v56, v186
	v_pk_mul_f32 v[54:55], v[54:55], v[56:57] op_sel_hi:[1,0]
	v_pk_mul_f32 v[52:53], v[52:53], v[56:57] op_sel_hi:[1,0]
	v_add_u32_e32 v56, v72, v120
	v_mad_i64_i32 v[56:57], s[4:5], v56, s37, v[124:125]
	v_lshl_add_u64 v[56:57], v[56:57], 0, v[60:61]
	v_cvt_pk_bf16_f32 v52, v52, s0
	global_store_short v[56:57], v52, off
	v_add_co_u32_e32 v52, vcc, s91, v56
	v_cvt_pk_bf16_f32 v58, v53, s0
	s_nop 0
	v_addc_co_u32_e32 v53, vcc, 0, v57, vcc
	global_store_short v[52:53], v58, off offset:512
	v_add_co_u32_e32 v52, vcc, s76, v56
	v_cvt_pk_bf16_f32 v54, v54, s0
	s_nop 0
	v_addc_co_u32_e32 v53, vcc, 0, v57, vcc
	global_store_short v[52:53], v54, off offset:1024
	v_add_co_u32_e32 v52, vcc, s34, v56
	v_cvt_pk_bf16_f32 v54, v55, s0
	s_nop 0
	v_addc_co_u32_e32 v53, vcc, 0, v57, vcc
	global_store_short v[52:53], v54, off offset:1536
	v_mov_b32_e32 v52, v186
	v_pk_mul_f32 v[50:51], v[50:51], v[52:53] op_sel_hi:[1,0]
	v_pk_mul_f32 v[48:49], v[48:49], v[52:53] op_sel_hi:[1,0]
	v_add_u32_e32 v52, v73, v120
	v_mad_i64_i32 v[52:53], s[4:5], v52, s37, v[124:125]
	v_lshl_add_u64 v[52:53], v[52:53], 0, v[60:61]
	v_cvt_pk_bf16_f32 v48, v48, s0
	global_store_short v[52:53], v48, off
	v_add_co_u32_e32 v48, vcc, s91, v52
	v_cvt_pk_bf16_f32 v54, v49, s0
	s_nop 0
	v_addc_co_u32_e32 v49, vcc, 0, v53, vcc
	global_store_short v[48:49], v54, off offset:512
	v_add_co_u32_e32 v48, vcc, s76, v52
	v_cvt_pk_bf16_f32 v50, v50, s0
	s_nop 0
	v_addc_co_u32_e32 v49, vcc, 0, v53, vcc
	global_store_short v[48:49], v50, off offset:1024
	v_add_co_u32_e32 v48, vcc, s34, v52
	v_cvt_pk_bf16_f32 v50, v51, s0
	s_nop 0
	v_addc_co_u32_e32 v49, vcc, 0, v53, vcc
	global_store_short v[48:49], v50, off offset:1536
	v_add_u32_e32 v48, 0x90, v171
	v_mul_hi_i32 v49, v48, s31
	v_lshrrev_b32_e32 v50, 31, v49
	v_ashrrev_i32_e32 v49, 11, v49
	v_add_u32_e32 v49, v49, v50
	v_mad_i32_i24 v50, v49, s36, v48
	v_lshlrev_b32_e32 v48, 1, v48
	v_lshlrev_b32_e32 v56, 10, v49
	v_ashrrev_i32_e32 v49, 31, v48
	v_lshl_add_u64 v[48:49], v[48:49], 2, s[40:41]
	global_load_dword v52, v[48:49], off offset:4
	v_ashrrev_i32_e32 v51, 31, v50
	v_or_b32_e32 v57, 16, v56
	s_waitcnt vmcnt(0)
	v_mov_b32_e32 v187, v52
	v_pk_mul_f32 v[46:47], v[46:47], v[52:53] op_sel_hi:[1,0]
	v_pk_mul_f32 v[52:53], v[44:45], v[52:53] op_sel_hi:[1,0]
	v_add_u32_e32 v44, v56, v170
	v_mad_i64_i32 v[54:55], s[4:5], v44, s37, v[124:125]
	v_lshlrev_b64 v[44:45], 1, v[50:51]
	v_lshl_add_u64 v[50:51], v[54:55], 0, v[44:45]
	v_cvt_pk_bf16_f32 v52, v52, s0
	global_store_short v[50:51], v52, off
	v_add_co_u32_e32 v52, vcc, s91, v50
	v_cvt_pk_bf16_f32 v54, v53, s0
	s_nop 0
	v_addc_co_u32_e32 v53, vcc, 0, v51, vcc
	global_store_short v[52:53], v54, off offset:512
	v_add_co_u32_e32 v52, vcc, s76, v50
	v_cvt_pk_bf16_f32 v46, v46, s0
	s_nop 0
	v_addc_co_u32_e32 v53, vcc, 0, v51, vcc
	global_store_short v[52:53], v46, off offset:1024
	v_add_co_u32_e32 v46, vcc, s34, v50
	v_cvt_pk_bf16_f32 v52, v47, s0
	s_nop 0
	v_addc_co_u32_e32 v47, vcc, 0, v51, vcc
	global_store_short v[46:47], v52, off offset:1536
	v_mov_b32_e32 v46, v187
	v_pk_mul_f32 v[42:43], v[42:43], v[46:47] op_sel_hi:[1,0]
	v_pk_mul_f32 v[40:41], v[40:41], v[46:47] op_sel_hi:[1,0]
	v_add_u32_e32 v46, v57, v170
	v_mad_i64_i32 v[46:47], s[4:5], v46, s37, v[124:125]
	v_lshl_add_u64 v[46:47], v[46:47], 0, v[44:45]
	v_cvt_pk_bf16_f32 v40, v40, s0
	global_store_short v[46:47], v40, off
	v_add_co_u32_e32 v40, vcc, s91, v46
	v_cvt_pk_bf16_f32 v50, v41, s0
	s_nop 0
	v_addc_co_u32_e32 v41, vcc, 0, v47, vcc
	global_store_short v[40:41], v50, off offset:512
	v_add_co_u32_e32 v40, vcc, s76, v46
	v_cvt_pk_bf16_f32 v42, v42, s0
	s_nop 0
	v_addc_co_u32_e32 v41, vcc, 0, v47, vcc
	global_store_short v[40:41], v42, off offset:1024
	v_add_co_u32_e32 v40, vcc, s34, v46
	v_cvt_pk_bf16_f32 v42, v43, s0
	s_nop 0
	v_addc_co_u32_e32 v41, vcc, 0, v47, vcc
	global_store_short v[40:41], v42, off offset:1536
	v_mov_b32_e32 v40, v187
	v_pk_mul_f32 v[38:39], v[38:39], v[40:41] op_sel_hi:[1,0]
	v_pk_mul_f32 v[36:37], v[36:37], v[40:41] op_sel_hi:[1,0]
	v_add_u32_e32 v40, v56, v120
	v_mad_i64_i32 v[40:41], s[4:5], v40, s37, v[124:125]
	v_lshl_add_u64 v[40:41], v[40:41], 0, v[44:45]
	v_cvt_pk_bf16_f32 v36, v36, s0
	global_store_short v[40:41], v36, off
	v_add_co_u32_e32 v36, vcc, s91, v40
	v_cvt_pk_bf16_f32 v42, v37, s0
	s_nop 0
	v_addc_co_u32_e32 v37, vcc, 0, v41, vcc
	global_store_short v[36:37], v42, off offset:512
	v_add_co_u32_e32 v36, vcc, s76, v40
	v_cvt_pk_bf16_f32 v38, v38, s0
	s_nop 0
	v_addc_co_u32_e32 v37, vcc, 0, v41, vcc
	global_store_short v[36:37], v38, off offset:1024
	v_add_co_u32_e32 v36, vcc, s34, v40
	v_cvt_pk_bf16_f32 v38, v39, s0
	s_nop 0
	v_addc_co_u32_e32 v37, vcc, 0, v41, vcc
	global_store_short v[36:37], v38, off offset:1536
	v_mov_b32_e32 v36, v187
	v_pk_mul_f32 v[34:35], v[34:35], v[36:37] op_sel_hi:[1,0]
	v_pk_mul_f32 v[32:33], v[32:33], v[36:37] op_sel_hi:[1,0]
	v_add_u32_e32 v36, v57, v120
	v_mad_i64_i32 v[36:37], s[4:5], v36, s37, v[124:125]
	v_lshl_add_u64 v[36:37], v[36:37], 0, v[44:45]
	v_cvt_pk_bf16_f32 v32, v32, s0
	global_store_short v[36:37], v32, off
	v_add_co_u32_e32 v32, vcc, s91, v36
	v_cvt_pk_bf16_f32 v38, v33, s0
	s_nop 0
	v_addc_co_u32_e32 v33, vcc, 0, v37, vcc
	global_store_short v[32:33], v38, off offset:512
	v_add_co_u32_e32 v32, vcc, s76, v36
	v_cvt_pk_bf16_f32 v34, v34, s0
	s_nop 0
	v_addc_co_u32_e32 v33, vcc, 0, v37, vcc
	global_store_short v[32:33], v34, off offset:1024
	v_add_co_u32_e32 v32, vcc, s34, v36
	v_cvt_pk_bf16_f32 v34, v35, s0
	s_nop 0
	v_addc_co_u32_e32 v33, vcc, 0, v37, vcc
	global_store_short v[32:33], v34, off offset:1536
	v_add_u32_e32 v32, 0xa0, v171
	v_mul_hi_i32 v33, v32, s31
	v_lshrrev_b32_e32 v34, 31, v33
	v_ashrrev_i32_e32 v33, 11, v33
	v_add_u32_e32 v33, v33, v34
	v_mad_i32_i24 v34, v33, s36, v32
	v_lshlrev_b32_e32 v32, 1, v32
	v_lshlrev_b32_e32 v40, 10, v33
	v_ashrrev_i32_e32 v33, 31, v32
	v_lshl_add_u64 v[32:33], v[32:33], 2, s[40:41]
	global_load_dword v36, v[32:33], off offset:4
	v_ashrrev_i32_e32 v35, 31, v34
	v_or_b32_e32 v41, 16, v40
	s_waitcnt vmcnt(0)
	v_mov_b32_e32 v188, v36
	v_pk_mul_f32 v[30:31], v[30:31], v[36:37] op_sel_hi:[1,0]
	v_pk_mul_f32 v[36:37], v[28:29], v[36:37] op_sel_hi:[1,0]
	v_add_u32_e32 v28, v40, v170
	v_mad_i64_i32 v[38:39], s[4:5], v28, s37, v[124:125]
	v_lshlrev_b64 v[28:29], 1, v[34:35]
	v_lshl_add_u64 v[34:35], v[38:39], 0, v[28:29]
	v_cvt_pk_bf16_f32 v36, v36, s0
	global_store_short v[34:35], v36, off
	v_add_co_u32_e32 v36, vcc, s91, v34
	v_cvt_pk_bf16_f32 v38, v37, s0
	s_nop 0
	v_addc_co_u32_e32 v37, vcc, 0, v35, vcc
	global_store_short v[36:37], v38, off offset:512
	v_add_co_u32_e32 v36, vcc, s76, v34
	v_cvt_pk_bf16_f32 v30, v30, s0
	s_nop 0
	v_addc_co_u32_e32 v37, vcc, 0, v35, vcc
	global_store_short v[36:37], v30, off offset:1024
	v_add_co_u32_e32 v30, vcc, s34, v34
	v_cvt_pk_bf16_f32 v36, v31, s0
	s_nop 0
	v_addc_co_u32_e32 v31, vcc, 0, v35, vcc
	global_store_short v[30:31], v36, off offset:1536
	v_mov_b32_e32 v30, v188
	v_pk_mul_f32 v[26:27], v[26:27], v[30:31] op_sel_hi:[1,0]
	v_pk_mul_f32 v[24:25], v[24:25], v[30:31] op_sel_hi:[1,0]
	v_add_u32_e32 v30, v41, v170
	v_mad_i64_i32 v[30:31], s[4:5], v30, s37, v[124:125]
	v_lshl_add_u64 v[30:31], v[30:31], 0, v[28:29]
	v_cvt_pk_bf16_f32 v24, v24, s0
	global_store_short v[30:31], v24, off
	v_add_co_u32_e32 v24, vcc, s91, v30
	v_cvt_pk_bf16_f32 v34, v25, s0
	s_nop 0
	v_addc_co_u32_e32 v25, vcc, 0, v31, vcc
	global_store_short v[24:25], v34, off offset:512
	v_add_co_u32_e32 v24, vcc, s76, v30
	v_cvt_pk_bf16_f32 v26, v26, s0
	s_nop 0
	v_addc_co_u32_e32 v25, vcc, 0, v31, vcc
	global_store_short v[24:25], v26, off offset:1024
	v_add_co_u32_e32 v24, vcc, s34, v30
	v_cvt_pk_bf16_f32 v26, v27, s0
	s_nop 0
	v_addc_co_u32_e32 v25, vcc, 0, v31, vcc
	global_store_short v[24:25], v26, off offset:1536
	v_mov_b32_e32 v24, v188
	v_pk_mul_f32 v[22:23], v[22:23], v[24:25] op_sel_hi:[1,0]
	v_pk_mul_f32 v[20:21], v[20:21], v[24:25] op_sel_hi:[1,0]
	v_add_u32_e32 v24, v40, v120
	v_mad_i64_i32 v[24:25], s[4:5], v24, s37, v[124:125]
	v_lshl_add_u64 v[24:25], v[24:25], 0, v[28:29]
	v_cvt_pk_bf16_f32 v20, v20, s0
	global_store_short v[24:25], v20, off
	v_add_co_u32_e32 v20, vcc, s91, v24
	v_cvt_pk_bf16_f32 v26, v21, s0
	s_nop 0
	v_addc_co_u32_e32 v21, vcc, 0, v25, vcc
	global_store_short v[20:21], v26, off offset:512
	v_add_co_u32_e32 v20, vcc, s76, v24
	v_cvt_pk_bf16_f32 v22, v22, s0
	s_nop 0
	v_addc_co_u32_e32 v21, vcc, 0, v25, vcc
	global_store_short v[20:21], v22, off offset:1024
	v_add_co_u32_e32 v20, vcc, s34, v24
	v_cvt_pk_bf16_f32 v22, v23, s0
	s_nop 0
	v_addc_co_u32_e32 v21, vcc, 0, v25, vcc
	global_store_short v[20:21], v22, off offset:1536
	v_mov_b32_e32 v20, v188
	v_pk_mul_f32 v[18:19], v[18:19], v[20:21] op_sel_hi:[1,0]
	v_pk_mul_f32 v[16:17], v[16:17], v[20:21] op_sel_hi:[1,0]
	v_add_u32_e32 v20, v41, v120
	v_mad_i64_i32 v[20:21], s[4:5], v20, s37, v[124:125]
	v_lshl_add_u64 v[20:21], v[20:21], 0, v[28:29]
	v_cvt_pk_bf16_f32 v16, v16, s0
	global_store_short v[20:21], v16, off
	v_add_co_u32_e32 v16, vcc, s91, v20
	v_cvt_pk_bf16_f32 v22, v17, s0
	s_nop 0
	v_addc_co_u32_e32 v17, vcc, 0, v21, vcc
	global_store_short v[16:17], v22, off offset:512
	v_add_co_u32_e32 v16, vcc, s76, v20
	v_cvt_pk_bf16_f32 v18, v18, s0
	s_nop 0
	v_addc_co_u32_e32 v17, vcc, 0, v21, vcc
	global_store_short v[16:17], v18, off offset:1024
	v_add_co_u32_e32 v16, vcc, s34, v20
	v_cvt_pk_bf16_f32 v18, v19, s0
	s_nop 0
	v_addc_co_u32_e32 v17, vcc, 0, v21, vcc
	global_store_short v[16:17], v18, off offset:1536
	v_add_u32_e32 v16, 0xb0, v171
	v_mul_hi_i32 v17, v16, s31
	v_lshrrev_b32_e32 v18, 31, v17
	v_ashrrev_i32_e32 v17, 11, v17
	v_add_u32_e32 v17, v17, v18
	v_mad_i32_i24 v18, v17, s36, v16
	v_lshlrev_b32_e32 v16, 1, v16
	v_lshlrev_b32_e32 v24, 10, v17
	v_ashrrev_i32_e32 v17, 31, v16
	v_lshl_add_u64 v[16:17], v[16:17], 2, s[40:41]
	global_load_dword v20, v[16:17], off offset:4
	v_ashrrev_i32_e32 v19, 31, v18
	v_or_b32_e32 v25, 16, v24
	s_waitcnt vmcnt(0)
	v_mov_b32_e32 v189, v20
	v_pk_mul_f32 v[14:15], v[14:15], v[20:21] op_sel_hi:[1,0]
	v_pk_mul_f32 v[20:21], v[12:13], v[20:21] op_sel_hi:[1,0]
	v_add_u32_e32 v12, v24, v170
	v_mad_i64_i32 v[22:23], s[4:5], v12, s37, v[124:125]
	v_lshlrev_b64 v[12:13], 1, v[18:19]
	v_lshl_add_u64 v[18:19], v[22:23], 0, v[12:13]
	v_cvt_pk_bf16_f32 v20, v20, s0
	global_store_short v[18:19], v20, off
	v_add_co_u32_e32 v20, vcc, s91, v18
	v_cvt_pk_bf16_f32 v22, v21, s0
	s_nop 0
	v_addc_co_u32_e32 v21, vcc, 0, v19, vcc
	global_store_short v[20:21], v22, off offset:512
	v_add_co_u32_e32 v20, vcc, s76, v18
	v_cvt_pk_bf16_f32 v14, v14, s0
	s_nop 0
	v_addc_co_u32_e32 v21, vcc, 0, v19, vcc
	global_store_short v[20:21], v14, off offset:1024
	v_add_co_u32_e32 v14, vcc, s34, v18
	v_cvt_pk_bf16_f32 v20, v15, s0
	s_nop 0
	v_addc_co_u32_e32 v15, vcc, 0, v19, vcc
	global_store_short v[14:15], v20, off offset:1536
	v_mov_b32_e32 v14, v189
	v_pk_mul_f32 v[10:11], v[10:11], v[14:15] op_sel_hi:[1,0]
	v_pk_mul_f32 v[8:9], v[8:9], v[14:15] op_sel_hi:[1,0]
	v_add_u32_e32 v14, v25, v170
	v_mad_i64_i32 v[14:15], s[4:5], v14, s37, v[124:125]
	v_lshl_add_u64 v[14:15], v[14:15], 0, v[12:13]
	v_cvt_pk_bf16_f32 v8, v8, s0
	global_store_short v[14:15], v8, off
	v_add_co_u32_e32 v8, vcc, s91, v14
	v_cvt_pk_bf16_f32 v18, v9, s0
	s_nop 0
	v_addc_co_u32_e32 v9, vcc, 0, v15, vcc
	global_store_short v[8:9], v18, off offset:512
	v_add_co_u32_e32 v8, vcc, s76, v14
	v_cvt_pk_bf16_f32 v10, v10, s0
	s_nop 0
	v_addc_co_u32_e32 v9, vcc, 0, v15, vcc
	global_store_short v[8:9], v10, off offset:1024
	v_add_co_u32_e32 v8, vcc, s34, v14
	v_cvt_pk_bf16_f32 v10, v11, s0
	s_nop 0
	v_addc_co_u32_e32 v9, vcc, 0, v15, vcc
	global_store_short v[8:9], v10, off offset:1536
	v_mov_b32_e32 v8, v189
	v_pk_mul_f32 v[6:7], v[6:7], v[8:9] op_sel_hi:[1,0]
	v_pk_mul_f32 v[4:5], v[4:5], v[8:9] op_sel_hi:[1,0]
	v_add_u32_e32 v8, v24, v120
	v_mad_i64_i32 v[8:9], s[4:5], v8, s37, v[124:125]
	v_lshl_add_u64 v[8:9], v[8:9], 0, v[12:13]
	v_cvt_pk_bf16_f32 v4, v4, s0
	global_store_short v[8:9], v4, off
	v_add_co_u32_e32 v4, vcc, s91, v8
	v_cvt_pk_bf16_f32 v10, v5, s0
	s_nop 0
	v_addc_co_u32_e32 v5, vcc, 0, v9, vcc
	global_store_short v[4:5], v10, off offset:512
	v_add_co_u32_e32 v4, vcc, s76, v8
	v_cvt_pk_bf16_f32 v6, v6, s0
	s_nop 0
	v_addc_co_u32_e32 v5, vcc, 0, v9, vcc
	global_store_short v[4:5], v6, off offset:1024
	v_add_co_u32_e32 v4, vcc, s34, v8
	v_cvt_pk_bf16_f32 v6, v7, s0
	s_nop 0
	v_addc_co_u32_e32 v5, vcc, 0, v9, vcc
	global_store_short v[4:5], v6, off offset:1536
	v_mov_b32_e32 v4, v189
	v_pk_mul_f32 v[2:3], v[2:3], v[4:5] op_sel_hi:[1,0]
	v_pk_mul_f32 v[0:1], v[0:1], v[4:5] op_sel_hi:[1,0]
	v_add_u32_e32 v4, v25, v120
	v_mad_i64_i32 v[4:5], s[4:5], v4, s37, v[124:125]
	v_lshl_add_u64 v[4:5], v[4:5], 0, v[12:13]
	v_cvt_pk_bf16_f32 v0, v0, s0
	global_store_short v[4:5], v0, off
	v_add_co_u32_e32 v0, vcc, s91, v4
	v_cvt_pk_bf16_f32 v6, v1, s0
	s_nop 0
	v_addc_co_u32_e32 v1, vcc, 0, v5, vcc
	global_store_short v[0:1], v6, off offset:512
	v_add_co_u32_e32 v0, vcc, 0x8000, v4
	v_cvt_pk_bf16_f32 v2, v2, s0
	s_nop 0
	v_addc_co_u32_e32 v1, vcc, 0, v5, vcc
	global_store_short v[0:1], v2, off offset:1024
	v_add_co_u32_e32 v0, vcc, 0xc000, v4
	v_cvt_pk_bf16_f32 v2, v3, s0
	s_nop 0
	v_addc_co_u32_e32 v1, vcc, 0, v5, vcc
	global_store_short v[0:1], v2, off offset:1536
	s_mov_b64 s[4:5], -1
	s_andn2_b64 vcc, exec, s[10:11]
	s_cbranch_vccnz .LBB0_2620
	s_andn2_b64 vcc, exec, s[14:15]
	s_cbranch_vccnz .LBB0_2619
	s_barrier
	s_branch .LBB0_2619
